# norm / norm-mix phases: wave enumeration keeps consecutive runs inside a workgroup (halo rows in one L2) and gives the extra third trip to wave 0 of every workgroup
# speedup vs baseline: 1.0200x; 1.0150x over previous
; __device__ __forceinline__ void phase_norm_mix(const Fr& F, int l, int jr, int nmix, int n0, int n1, int n2, int n3) {
;     const int nidx[4] = {n0, n1, n2, n3};
;     for (int run = F.gw; run < NT / 4; run += GRID * NWAVES) {
;         const int m0 = run * 4, b = m0 / TB, t0 = m0 - b * TB, seg_lo = b * TB + (t0 < CTXL ? 0 : CTXL), seg_hi = b * TB + (t0 < CTXL ? CTXL : TB);
;         f32x4 h[6][4];
;         load_rows<6>(F, l, m0 - 1, seg_lo, seg_hi, h); norm_rows<6>(F, l, m0, h);
.LBB0_48:
	s_cmpk_lt_i32 s36, 0x1100
	v_cmp_gt_i32_e32 vcc, 2, v1
	s_cselect_b64 s[38:39], -1, 0
	v_cmp_lt_i32_e64 s[6:7], 1, v2
	s_and_b64 s[8:9], vcc, s[38:39]
	s_and_b64 s[6:7], s[8:9], s[6:7]
	v_lshlrev_b32_e32 v132, 4, v130
	v_lshlrev_b32_e32 v134, 3, v130
	s_and_saveexec_b64 s[8:9], s[6:7]
	s_cbranch_execz .LBB0_106
	s_load_dwordx2 s[6:7], s[0:1], 0x20
	s_load_dwordx2 s[10:11], s[0:1], 0x38
	v_mov_b32_e32 v113, 0
	v_mov_b32_e32 v133, v113
	v_mov_b32_e32 v135, v113
	s_waitcnt lgkmcnt(0)
	v_lshl_add_u64 v[114:115], s[6:7], 0, v[132:133]
	v_lshl_add_u64 v[0:1], s[26:27], 0, v[134:135]
	s_mov_b64 s[6:7], 0x1200000
	v_lshl_add_u64 v[118:119], v[0:1], 0, s[6:7]
	s_mov_b64 s[6:7], 0x3400000
	v_lshl_add_u64 v[116:117], s[10:11], 0, v[132:133]
	v_lshl_add_u64 v[122:123], v[0:1], 0, s[6:7]
	s_mov_b64 s[6:7], 0x4000
	v_lshl_add_u64 v[124:125], v[116:117], 0, s[6:7]
	s_mov_b64 s[6:7], 0x5600000
	v_lshl_add_u64 v[126:127], v[0:1], 0, s[6:7]
	s_mov_b64 s[6:7], 0x5000
	s_add_u32 s10, s0, 16
	v_lshl_add_u64 v[136:137], v[116:117], 0, s[6:7]
	s_mov_b64 s[6:7], 0x7800000
	s_addc_u32 s11, s1, 0
	s_mov_b64 s[12:13], 0x1000
	v_lshl_add_u64 v[138:139], v[0:1], 0, s[6:7]
	s_mul_i32 s3, s2, 28
	s_lshl_b32 s6, s68, 2
	v_lshl_add_u64 v[120:121], v[116:117], 0, s[12:13]
	s_add_i32 s14, s3, s6
	s_addk_i32 s14, 0x3fc
	s_lshl_b32 s95, s2, 2
	s_cmp_eq_u32 s68, 0
	s_cselect_b32 s14, s95, s14
	s_movk_i32 s3, 0x100
	v_lshlrev_b32_e32 v112, 4, v130
	s_movk_i32 s37, 0x1000
	v_mov_b32_e32 v129, 0x358637bd
	s_mov_b32 s48, 0xf800000
	v_mov_b32_e32 v131, 0x260
	s_mul_i32 s49, s2, 7
	s_add_i32 s49, s49, s68
	s_addk_i32 s49, 0xff
	s_cmp_eq_u32 s68, 0
	s_cselect_b32 s49, s2, s49
	s_branch .LBB0_52

; __device__ __forceinline__ void phase_norm_mix(const Fr& F, int l, int jr, int nmix, int n0, int n1, int n2, int n3) {
;     const int nidx[4] = {n0, n1, n2, n3};
;     for (int run = F.gw; run < NT / 4; run += GRID * NWAVES) {
;         const int m0 = run * 4, b = m0 / TB, t0 = m0 - b * TB, seg_lo = b * TB + (t0 < CTXL ? 0 : CTXL), seg_hi = b * TB + (t0 < CTXL ? CTXL : TB);
;         f32x4 h[6][4];
;         load_rows<6>(F, l, m0 - 1, seg_lo, seg_hi, h); norm_rows<6>(F, l, m0, h);
.LBB0_303:
	s_or_b64 exec, exec, s[6:7]
	v_cmp_gt_i32_e32 vcc, 4, v1
	v_cmp_lt_i32_e64 s[6:7], 3, v2
	s_and_b64 s[6:7], vcc, s[6:7]
	s_and_b64 s[6:7], s[6:7], s[38:39]
	s_and_saveexec_b64 s[8:9], s[6:7]
	s_cbranch_execz .LBB0_361
	s_load_dwordx2 s[6:7], s[0:1], 0x20
	s_load_dwordx2 s[10:11], s[0:1], 0x38
	v_mov_b32_e32 v113, 0
	v_mov_b32_e32 v133, v113
	v_mov_b32_e32 v135, v113
	s_waitcnt lgkmcnt(0)
	v_lshl_add_u64 v[114:115], s[6:7], 0, v[132:133]
	v_lshl_add_u64 v[0:1], s[10:11], 0, v[132:133]
	s_mov_b64 s[6:7], 0x2000
	v_lshl_add_u64 v[116:117], v[0:1], 0, s[6:7]
	v_lshl_add_u64 v[2:3], s[26:27], 0, v[134:135]
	s_mov_b64 s[6:7], 0x1200000
	v_lshl_add_u64 v[118:119], v[2:3], 0, s[6:7]
	s_mov_b64 s[6:7], 0x3000
	s_add_u32 s10, s0, 16
	v_lshl_add_u64 v[120:121], v[0:1], 0, s[6:7]
	s_mov_b64 s[6:7], 0x3400000
	s_addc_u32 s11, s1, 0
	v_lshl_add_u64 v[122:123], v[2:3], 0, s[6:7]
	s_mul_i32 s3, s2, 28
	s_lshl_b32 s6, s68, 2
	s_add_i32 s12, s3, s6
	s_addk_i32 s12, 0x3fc
	s_lshl_b32 s95, s2, 2
	s_cmp_eq_u32 s68, 0
	s_cselect_b32 s12, s95, s12
	s_movk_i32 s3, 0x100
	v_lshlrev_b32_e32 v112, 4, v130
	s_mov_b64 s[14:15], 0x1000
	s_movk_i32 s37, 0x1000
	v_mov_b32_e32 v129, 0x358637bd
	s_mov_b32 s48, 0xf800000
	v_mov_b32_e32 v131, 0x260
	s_mul_i32 s49, s2, 7
	s_add_i32 s49, s49, s68
	s_addk_i32 s49, 0xff
	s_cmp_eq_u32 s68, 0
	s_cselect_b32 s49, s2, s49
	s_branch .LBB0_307

; __device__ __forceinline__ void phase_norm_plain(const Fr& F, int l) {
;     for (int run = F.gw; run < NT / 4; run += GRID * NWAVES) {
;         const int m0 = run * 4; f32x4 h[4][4];
;         load_rows<4>(F, l, m0, 0, NT, h); norm_rows<4>(F, l, m0, h);
.LBB0_828:
	s_cmp_lt_i32 s34, 9
	s_cselect_b64 s[6:7], -1, 0
	s_cmp_gt_i32 s35, 8
	s_cselect_b64 s[8:9], -1, 0
	s_and_b64 s[6:7], s[6:7], s[8:9]
	s_and_b64 s[6:7], s[6:7], s[38:39]
	s_andn2_b64 vcc, exec, s[6:7]
	s_cbranch_vccnz .LBB0_863
	s_load_dwordx2 s[6:7], s[0:1], 0x20
	s_load_dwordx2 s[8:9], s[0:1], 0x130
	v_mov_b32_e32 v81, 0
	s_add_u32 s3, s26, 0xf000
	v_mov_b32_e32 v133, v81
	s_addc_u32 s24, s27, 0
	s_waitcnt lgkmcnt(0)
	v_lshl_add_u64 v[0:1], s[6:7], 0, v[132:133]
	s_mov_b64 s[10:11], 0x1000
	v_mov_b32_e32 v135, v81
	v_lshl_add_u64 v[82:83], v[0:1], 0, s[10:11]
	v_lshl_add_u64 v[0:1], s[26:27], 0, v[134:135]
	s_mov_b64 s[6:7], 0x1200000
	s_add_u32 s12, s26, 0x300000
	v_lshl_add_u64 v[84:85], v[0:1], 0, s[6:7]
	s_addc_u32 s13, s27, 0
	s_mul_i32 s6, s2, 28
	s_lshl_b32 s7, s68, 2
	s_add_i32 s6, s6, s7
	s_addk_i32 s6, 0x3fc
	s_lshl_b32 s95, s2, 2
	s_cmp_eq_u32 s68, 0
	s_cselect_b32 s6, s95, s6
	s_or_b32 s14, s6, 3
	v_lshlrev_b32_e32 v80, 4, v130
	s_movk_i32 s25, 0x1000
	v_mov_b32_e32 v102, 0x358637bd
	s_mov_b32 s42, 0xf800000
	v_mov_b32_e32 v103, 0x260
	s_mul_i32 s43, s2, 7
	s_add_i32 s43, s43, s68
	s_addk_i32 s43, 0xff
	s_cmp_eq_u32 s68, 0
	s_cselect_b32 s43, s2, s43
	s_branch .LBB0_831

; __device__ __forceinline__ void phase_norm_plain(const Fr& F, int l) {
;     for (int run = F.gw; run < NT / 4; run += GRID * NWAVES) {
;         const int m0 = run * 4; f32x4 h[4][4];
;         load_rows<4>(F, l, m0, 0, NT, h); norm_rows<4>(F, l, m0, h);
.LBB0_1332:
	s_cmp_lt_i32 s34, 14
	s_cselect_b64 s[6:7], -1, 0
	s_cmp_gt_i32 s35, 13
	s_cselect_b64 s[8:9], -1, 0
	s_and_b64 s[6:7], s[6:7], s[8:9]
	s_and_b64 s[6:7], s[6:7], s[38:39]
	s_andn2_b64 vcc, exec, s[6:7]
	s_cbranch_vccnz .LBB0_1367
	s_load_dwordx2 s[6:7], s[0:1], 0x20
	s_load_dwordx2 s[8:9], s[0:1], 0x130
	v_mov_b32_e32 v81, 0
	s_add_u32 s3, s26, 0x1e000
	v_mov_b32_e32 v133, v81
	s_addc_u32 s24, s27, 0
	s_waitcnt lgkmcnt(0)
	v_lshl_add_u64 v[0:1], s[6:7], 0, v[132:133]
	s_mov_b64 s[6:7], 0x2000
	v_mov_b32_e32 v135, v81
	v_lshl_add_u64 v[82:83], v[0:1], 0, s[6:7]
	v_lshl_add_u64 v[0:1], s[26:27], 0, v[134:135]
	s_mov_b64 s[6:7], 0x1200000
	s_add_u32 s10, s26, 0x300000
	v_lshl_add_u64 v[84:85], v[0:1], 0, s[6:7]
	s_addc_u32 s11, s27, 0
	s_mul_i32 s6, s2, 28
	s_lshl_b32 s7, s68, 2
	s_add_i32 s6, s6, s7
	s_addk_i32 s6, 0x3fc
	s_lshl_b32 s95, s2, 2
	s_cmp_eq_u32 s68, 0
	s_cselect_b32 s6, s95, s6
	s_or_b32 s12, s6, 3
	v_lshlrev_b32_e32 v80, 4, v130
	s_mov_b64 s[14:15], 0x1000
	s_movk_i32 s25, 0x1000
	v_mov_b32_e32 v102, 0x358637bd
	s_mov_b32 s42, 0xf800000
	v_mov_b32_e32 v103, 0x260
	s_mul_i32 s43, s2, 7
	s_add_i32 s43, s43, s68
	s_addk_i32 s43, 0xff
	s_cmp_eq_u32 s68, 0
	s_cselect_b32 s43, s2, s43
	s_branch .LBB0_1335

; __device__ __forceinline__ void phase_norm_mix(const Fr& F, int l, int jr, int nmix, int n0, int n1, int n2, int n3) {
;     const int nidx[4] = {n0, n1, n2, n3};
;     for (int run = F.gw; run < NT / 4; run += GRID * NWAVES) {
;         const int m0 = run * 4, b = m0 / TB, t0 = m0 - b * TB, seg_lo = b * TB + (t0 < CTXL ? 0 : CTXL), seg_hi = b * TB + (t0 < CTXL ? CTXL : TB);
;         f32x4 h[6][4];
;         load_rows<6>(F, l, m0 - 1, seg_lo, seg_hi, h); norm_rows<6>(F, l, m0, h);
.LBB0_2028:
	s_cmp_lt_i32 s34, 22
	s_cselect_b64 s[6:7], -1, 0
	s_cmp_gt_i32 s35, 21
	s_cselect_b64 s[8:9], -1, 0
	s_and_b64 s[6:7], s[6:7], s[8:9]
	s_and_b64 s[6:7], s[6:7], s[38:39]
	s_andn2_b64 vcc, exec, s[6:7]
	s_cbranch_vccnz .LBB0_2085
	s_load_dwordx2 s[6:7], s[0:1], 0x20
	s_load_dwordx2 s[10:11], s[0:1], 0x38
	s_load_dwordx2 s[8:9], s[0:1], 0x130
	v_mov_b32_e32 v113, 0
	v_mov_b32_e32 v133, v113
	v_mov_b32_e32 v135, v113
	s_waitcnt lgkmcnt(0)
	v_lshl_add_u64 v[0:1], s[6:7], 0, v[132:133]
	s_mov_b64 s[6:7], 0x3000
	v_lshl_add_u64 v[114:115], v[0:1], 0, s[6:7]
	v_lshl_add_u64 v[0:1], s[10:11], 0, v[132:133]
	s_mov_b64 s[6:7], 0x6000
	v_lshl_add_u64 v[116:117], v[0:1], 0, s[6:7]
	v_lshl_add_u64 v[2:3], s[26:27], 0, v[134:135]
	s_mov_b64 s[6:7], 0x1200000
	v_lshl_add_u64 v[118:119], v[2:3], 0, s[6:7]
	s_mov_b64 s[6:7], 0x7000
	v_lshl_add_u64 v[120:121], v[0:1], 0, s[6:7]
	s_mov_b64 s[6:7], 0x3400000
	v_lshl_add_u64 v[122:123], v[2:3], 0, s[6:7]
	s_mov_b64 s[6:7], 0xa000
	s_add_u32 s3, s26, 0x2d000
	v_lshl_add_u64 v[124:125], v[0:1], 0, s[6:7]
	s_mov_b64 s[6:7], 0x5600000
	s_addc_u32 s37, s27, 0
	v_lshl_add_u64 v[126:127], v[2:3], 0, s[6:7]
	s_mov_b64 s[6:7], 0xb000
	s_add_u32 s10, s26, 0x300000
	v_lshl_add_u64 v[136:137], v[0:1], 0, s[6:7]
	s_mov_b64 s[6:7], 0x7800000
	s_addc_u32 s11, s27, 0
	v_lshl_add_u64 v[138:139], v[2:3], 0, s[6:7]
	s_mul_i32 s6, s2, 28
	s_lshl_b32 s7, s68, 2
	s_add_i32 s12, s6, s7
	s_addk_i32 s12, 0x3fc
	s_lshl_b32 s95, s2, 2
	s_cmp_eq_u32 s68, 0
	s_cselect_b32 s12, s95, s12
	s_movk_i32 s50, 0x100
	v_lshlrev_b32_e32 v112, 4, v130
	s_mov_b64 s[14:15], 0x1000
	s_movk_i32 s51, 0x1000
	v_mov_b32_e32 v129, 0x358637bd
	s_mov_b32 s52, 0xf800000
	v_mov_b32_e32 v133, 0x260
	s_mul_i32 s53, s2, 7
	s_add_i32 s53, s53, s68
	s_addk_i32 s53, 0xff
	s_cmp_eq_u32 s68, 0
	s_cselect_b32 s53, s2, s53
	s_branch .LBB0_2032

; __device__ __forceinline__ void phase_norm_mix(const Fr& F, int l, int jr, int nmix, int n0, int n1, int n2, int n3) {
;     const int nidx[4] = {n0, n1, n2, n3};
;     for (int run = F.gw; run < NT / 4; run += GRID * NWAVES) {
;         const int m0 = run * 4, b = m0 / TB, t0 = m0 - b * TB, seg_lo = b * TB + (t0 < CTXL ? 0 : CTXL), seg_hi = b * TB + (t0 < CTXL ? CTXL : TB);
;         f32x4 h[6][4];
;         load_rows<6>(F, l, m0 - 1, seg_lo, seg_hi, h); norm_rows<6>(F, l, m0, h);
.LBB0_2282:
	s_cmp_lt_i32 s34, 24
	s_cselect_b64 s[6:7], -1, 0
	s_cmp_gt_i32 s35, 23
	s_cselect_b64 s[8:9], -1, 0
	s_and_b64 s[6:7], s[6:7], s[8:9]
	s_and_b64 s[6:7], s[6:7], s[38:39]
	s_andn2_b64 vcc, exec, s[6:7]
	s_cbranch_vccnz .LBB0_2339
	s_load_dwordx2 s[6:7], s[0:1], 0x20
	s_load_dwordx2 s[10:11], s[0:1], 0x38
	s_load_dwordx2 s[8:9], s[0:1], 0x130
	v_mov_b32_e32 v135, 0
	v_mov_b32_e32 v133, v135
	s_add_u32 s3, s26, 0x2d000
	s_waitcnt lgkmcnt(0)
	v_lshl_add_u64 v[0:1], s[6:7], 0, v[132:133]
	s_mov_b64 s[6:7], 0x3000
	v_lshl_add_u64 v[112:113], v[0:1], 0, s[6:7]
	v_lshl_add_u64 v[0:1], s[10:11], 0, v[132:133]
	s_mov_b64 s[6:7], 0x8000
	v_lshl_add_u64 v[114:115], v[0:1], 0, s[6:7]
	v_lshl_add_u64 v[2:3], s[26:27], 0, v[134:135]
	s_mov_b64 s[6:7], 0x1200000
	s_addc_u32 s37, s27, 0
	v_lshl_add_u64 v[116:117], v[2:3], 0, s[6:7]
	s_mov_b64 s[6:7], 0x9000
	s_add_u32 s10, s26, 0x300000
	v_lshl_add_u64 v[118:119], v[0:1], 0, s[6:7]
	s_mov_b64 s[6:7], 0x3400000
	s_addc_u32 s11, s27, 0
	v_lshl_add_u64 v[120:121], v[2:3], 0, s[6:7]
	s_mul_i32 s6, s2, 28
	s_lshl_b32 s7, s68, 2
	s_add_i32 s12, s6, s7
	s_addk_i32 s12, 0x3fc
	s_lshl_b32 s95, s2, 2
	s_cmp_eq_u32 s68, 0
	s_cselect_b32 s12, s95, s12
	s_movk_i32 s48, 0x100
	v_lshlrev_b32_e32 v134, 4, v130
	s_mov_b64 s[14:15], 0x1000
	s_movk_i32 s49, 0x1000
	v_mov_b32_e32 v129, 0x358637bd
	s_mov_b32 s50, 0xf800000
	v_mov_b32_e32 v133, 0x260
	s_mul_i32 s51, s2, 7
	s_add_i32 s51, s51, s68
	s_addk_i32 s51, 0xff
	s_cmp_eq_u32 s68, 0
	s_cselect_b32 s51, s2, s51
	s_branch .LBB0_2286
